# in-phase hand-offs (SSD states, EpiFinal/mini_final ssq exchange): acquiring L1 invalidate issued by wave 1 while wave 0 polls
# speedup vs baseline: 1.0189x; 1.0034x over previous
.LBB0_178:
	s_or_b64 exec, exec, s[20:21]
	v_readfirstlane_b32 s100, v0
	s_lshr_b32 s100, s100, 6
	s_cmp_lg_u32 s100, 1
	s_cbranch_scc1 .Lef_noinv
	buffer_inv sc1
	s_waitcnt vmcnt(0)
.Lef_noinv:
	v_cmp_gt_i32_e32 vcc, 64, v4
	s_and_saveexec_b64 s[20:21], vcc
	s_cbranch_execz .LBB0_184
	s_mov_b32 s17, 0x100001
	s_branch .LBB0_181

.LBB0_181:
	s_waitcnt lgkmcnt(0)
	global_load_dword v5, v3, s[18:19] sc1
	s_waitcnt vmcnt(0)
	v_readfirstlane_b32 s22, v5
	s_cmp_gt_u32 s22, 3
	s_mov_b64 s[22:23], -1
	s_cbranch_scc1 .LBB0_180
	s_add_i32 s17, s17, -1
	s_cmp_eq_u32 s17, 0
	s_cselect_b64 s[22:23], -1, 0
	s_sleep 1
	s_branch .LBB0_180
.LBB0_183:
	s_nop 0
.LBB0_184:
	s_or_b64 exec, exec, s[20:21]
	s_waitcnt lgkmcnt(0)
	s_barrier
	v_cmp_gt_i32_e32 vcc, s85, v4
	s_and_saveexec_b64 s[18:19], vcc
	s_cbranch_execz .LBB0_186
	v_add_u32_e32 v6, s15, v4
	v_ashrrev_i32_e32 v7, 31, v6
	v_lshlrev_b64 v[6:7], 6, v[6:7]
	v_lshl_add_u64 v[18:19], s[54:55], 0, v[6:7]
	global_load_dwordx4 v[6:9], v[18:19], off
	global_load_dwordx4 v[10:13], v[18:19], off offset:32
	global_load_dwordx4 v[14:17], v[18:19], off offset:16
	global_load_dwordx4 v[100:103], v[18:19], off offset:48
	s_mov_b32 s15, 0x800000
	v_lshl_add_u32 v4, v4, 2, v225
	s_waitcnt vmcnt(3)
	v_mov_b32_e32 v18, v6
	s_waitcnt vmcnt(2)
	v_mov_b32_e32 v19, v10
	v_mov_b32_e32 v10, v7
	v_mov_b32_e32 v6, v8
	v_mov_b32_e32 v7, v12
	v_mov_b32_e32 v12, v9
	s_waitcnt vmcnt(1)
	v_mov_b32_e32 v8, v14
	s_waitcnt vmcnt(0)
	v_mov_b32_e32 v9, v100
	v_mov_b32_e32 v100, v15
	v_mov_b32_e32 v14, v16
	v_mov_b32_e32 v15, v102
	v_mov_b32_e32 v102, v17
	v_pk_add_f32 v[10:11], v[18:19], v[10:11]
	v_pk_add_f32 v[6:7], v[6:7], v[12:13]
	v_pk_add_f32 v[8:9], v[8:9], v[100:101]
	v_pk_add_f32 v[12:13], v[14:15], v[102:103]
	v_pk_add_f32 v[6:7], v[10:11], v[6:7]
	v_pk_add_f32 v[8:9], v[8:9], v[12:13]
	s_nop 0
	v_pk_add_f32 v[6:7], v[6:7], v[8:9]
	s_waitcnt lgkmcnt(0)
	v_add_f32_e32 v5, v6, v7
	v_fmamk_f32 v5, v5, 0x3a800000, v223
	v_mul_f32_e32 v6, 0x4b800000, v5
	v_cmp_gt_f32_e32 vcc, s15, v5
	s_nop 1
	v_cndmask_b32_e32 v5, v5, v6, vcc
	v_rsq_f32_e32 v5, v5
	s_nop 0
	v_mul_f32_e32 v6, 0x45800000, v5
	v_cndmask_b32_e32 v5, v5, v6, vcc
	ds_write_b32 v4, v5

.LBB0_213:
	s_or_b64 exec, exec, s[18:19]
	s_mov_b32 s100, s22
	s_lshr_b32 s100, s100, 6
	s_cmp_lg_u32 s100, 1
	s_cbranch_scc1 .Lmf_noinv
	buffer_inv sc1
	s_waitcnt vmcnt(0)
.Lmf_noinv:
	s_cmp_gt_u32 s22, 63
	s_cbranch_scc1 .LBB0_219
	s_mov_b32 s20, 0x100001
	s_branch .LBB0_216

.LBB0_216:
	global_load_dword v9, v3, s[16:17] sc1
	s_waitcnt vmcnt(0)
	v_readfirstlane_b32 s18, v9
	s_cmp_gt_u32 s18, 15
	s_mov_b64 s[18:19], -1
	s_cbranch_scc1 .LBB0_215
	s_add_i32 s20, s20, -1
	s_cmp_eq_u32 s20, 0
	s_cselect_b64 s[18:19], -1, 0
	s_sleep 1
	s_branch .LBB0_215
.LBB0_218:
	s_nop 0
.LBB0_219:
	s_barrier
	s_and_saveexec_b64 s[16:17], s[40:41]
	s_cbranch_execz .LBB0_221
	v_lshlrev_b64 v[4:5], 6, v[4:5]
	v_lshl_add_u64 v[4:5], s[14:15], 0, v[4:5]
	global_load_dwordx4 v[10:13], v[4:5], off
	global_load_dwordx4 v[14:17], v[4:5], off offset:32
	global_load_dwordx4 v[22:25], v[4:5], off offset:16
	global_load_dwordx4 v[26:29], v[4:5], off offset:48
	s_mov_b32 s14, 0x800000
	s_waitcnt vmcnt(3)
	v_mov_b32_e32 v4, v10
	s_waitcnt vmcnt(2)
	v_mov_b32_e32 v5, v14
	v_mov_b32_e32 v14, v11
	v_mov_b32_e32 v10, v12
	v_mov_b32_e32 v11, v16
	v_mov_b32_e32 v16, v13
	s_waitcnt vmcnt(1)
	v_mov_b32_e32 v12, v22
	s_waitcnt vmcnt(0)
	v_mov_b32_e32 v13, v26
	v_mov_b32_e32 v26, v23
	v_mov_b32_e32 v18, v24
	v_mov_b32_e32 v19, v28
	v_mov_b32_e32 v28, v25
	v_pk_add_f32 v[4:5], v[4:5], v[14:15]
	v_pk_add_f32 v[10:11], v[10:11], v[16:17]
	v_pk_add_f32 v[12:13], v[12:13], v[26:27]
	v_pk_add_f32 v[14:15], v[18:19], v[28:29]
	v_pk_add_f32 v[4:5], v[4:5], v[10:11]
	v_pk_add_f32 v[10:11], v[12:13], v[14:15]
	s_nop 0
	v_pk_add_f32 v[4:5], v[4:5], v[10:11]
	s_nop 0
	v_add_f32_e32 v4, v4, v5
	v_fmamk_f32 v4, v4, 0x3a800000, v223
	v_mul_f32_e32 v5, 0x4b800000, v4
	v_cmp_gt_f32_e32 vcc, s14, v4
	s_nop 1
	v_cndmask_b32_e32 v4, v4, v5, vcc
	v_rsq_f32_e32 v4, v4
	s_nop 0
	v_mul_f32_e32 v5, 0x45800000, v4
	v_cndmask_b32_e32 v4, v4, v5, vcc
	ds_write_b32 v7, v4 offset:33024

.LBB0_433:
	v_readlane_b32 s16, v253, 38
	v_readlane_b32 s17, v253, 39
	s_andn2_b64 vcc, exec, s[16:17]
	s_cbranch_vccnz .LBB0_453
	s_cmp_lt_u32 s14, 64
	s_mov_b64 s[14:15], -1
	s_cbranch_scc1 .LBB0_436
	v_mov_b32_e32 v61, v3
	s_mov_b64 s[14:15], 0
	v_readfirstlane_b32 s100, v0
	s_lshr_b32 s100, s100, 6
	s_cmp_lg_u32 s100, 1
	s_cbranch_scc1 .Lsd_noinv
	buffer_inv sc1
	s_waitcnt vmcnt(0)
.Lsd_noinv:
.LBB0_436:
	s_andn2_b64 vcc, exec, s[14:15]
	s_cbranch_vccnz .LBB0_444
	s_lshl_b32 s14, s48, 9
	v_readlane_b32 s15, v253, 50
	s_add_i32 s14, s14, s15
	s_ashr_i32 s15, s14, 31
	s_lshl_b64 s[14:15], s[14:15], 2
	s_add_u32 s14, s6, s14
	s_addc_u32 s15, s7, s15
	v_lshlrev_b32_e32 v28, 2, v60
	v_mov_b32_e32 v29, v3
	v_lshl_add_u64 v[28:29], s[14:15], 0, v[28:29]
	s_mov_b64 s[14:15], 0xc0000
	v_cmp_gt_u32_e64 s[38:39], s35, v60
	v_mov_b32_e32 v61, v3
	v_lshl_add_u64 v[28:29], v[28:29], 0, s[14:15]
	s_mov_b32 s23, 0x100001
	s_branch .LBB0_439

.LBB0_443:
	s_waitcnt vmcnt(0)
.LBB0_444:
	v_readlane_b32 s14, v253, 28
	s_add_i32 s14, s52, s14
	s_add_u32 s23, s6, 0x80000
	s_mul_i32 s14, s14, 7
	s_addc_u32 s30, s7, 0
	s_ashr_i32 s15, s14, 31
	s_lshl_b64 s[14:15], s[14:15], 14
	s_add_u32 s14, s4, s14
	s_addc_u32 s15, s5, s15
	s_lshl_b32 s16, s92, 12
	s_add_u32 s14, s14, s16
	s_waitcnt lgkmcnt(0)
	s_barrier
	s_addc_u32 s15, s15, 0
	v_lshl_add_u64 v[62:63], v[60:61], 3, s[14:15]
	global_load_dwordx2 v[112:113], v[62:63], off
	global_load_dwordx2 v[110:111], v[62:63], off offset:512
	global_load_dwordx2 v[108:109], v[62:63], off offset:1024
	global_load_dwordx2 v[106:107], v[62:63], off offset:1536
	global_load_dwordx2 v[104:105], v[62:63], off offset:2048
	global_load_dwordx2 v[102:103], v[62:63], off offset:2560
	global_load_dwordx2 v[100:101], v[62:63], off offset:3072
	global_load_dwordx2 v[98:99], v[62:63], off offset:3584
	v_mov_b32_e32 v30, v3
	v_mov_b32_e32 v31, v3
	s_mul_i32 s14, s18, 7
	v_readlane_b32 s15, v254, 2
	v_mov_b32_e32 v28, v3
	v_mov_b32_e32 v29, v3
	v_mov_b64_e32 v[46:47], v[30:31]
	v_mov_b64_e32 v[50:51], v[30:31]
	v_mov_b64_e32 v[58:59], v[30:31]
	v_mov_b64_e32 v[34:35], v[30:31]
	v_mov_b64_e32 v[42:43], v[30:31]
	v_mov_b64_e32 v[38:39], v[30:31]
	v_mov_b64_e32 v[54:55], v[30:31]
	s_add_i32 s31, s15, s14
	s_mov_b32 s34, 2
	v_mov_b64_e32 v[44:45], v[28:29]
	v_mov_b64_e32 v[48:49], v[28:29]
	v_mov_b64_e32 v[56:57], v[28:29]
	v_mov_b64_e32 v[32:33], v[28:29]
	v_mov_b64_e32 v[40:41], v[28:29]
	v_mov_b64_e32 v[36:37], v[28:29]
	v_mov_b64_e32 v[52:53], v[28:29]
